# MoBA gate: q-row loads issued at the top of the unit, overlapping the k-mean copy
# speedup vs baseline: 1.0029x; 1.0029x over previous
.LBB0_500:
	s_bfe_u32 s2, s21, 0x30005
	s_lshl_b32 s2, s2, 12
	s_lshl_b32 s3, s23, 8
	s_add_i32 s2, s2, s3
	v_ashrrev_i32_e32 v65, 1, v2
	v_add_u32_e32 v65, s2, v65
	v_readlane_b32 s2, v246, 26
	v_readlane_b32 s3, v246, 27
	v_and_b32_e32 v68, 1, v2
	v_lshlrev_b32_e32 v68, 6, v68
	v_mov_b64_e32 v[66:67], s[2:3]
	v_mad_u64_u32 v[66:67], vcc, v65, s20, v[66:67]
	s_bfe_u32 s2, s21, 0x30002
	s_lshl_b32 s2, s2, 7
	v_or_b32_e32 v68, s2, v68
	v_mov_b32_e32 v69, 0
	v_lshl_add_u64 v[66:67], v[66:67], 0, v[68:69]
	global_load_dwordx4 v[72:75], v[66:67], off
	global_load_dwordx4 v[76:79], v[66:67], off offset:16
	global_load_dwordx4 v[80:83], v[66:67], off offset:32
	global_load_dwordx4 v[84:87], v[66:67], off offset:48
	s_lshl_b32 s25, s23, 6
	s_bfe_u32 s24, s21, 0x30002
	v_cmp_le_i32_e32 vcc, s25, v2
	s_and_saveexec_b64 s[2:3], vcc
	s_xor_b64 s[2:3], exec, s[2:3]
	s_lshl_b32 s4, s24, 6
	s_or_saveexec_b64 s[2:3], s[2:3]
	s_bfe_u32 s26, s21, 0x30005
	v_mov_b64_e32 v[6:7], s[4:5]
	s_xor_b64 exec, exec, s[2:3]
	s_cbranch_execz .LBB0_516
	s_lshl_b32 s4, s26, 13
	s_lshl_b32 s8, s24, 8
	s_add_u32 s8, s16, s8
	v_and_b32_e32 v0, 63, v2
	s_addc_u32 s9, s17, 0
	v_lshlrev_b32_e32 v0, 2, v0
	v_add_u32_e32 v3, 0x200, v2
	v_lshl_add_u64 v[4:5], s[8:9], 0, v[0:1]
	v_max_i32_e32 v0, s25, v3
	v_xad_u32 v6, v2, -1, v0
	v_cmp_lt_u32_e32 vcc, s15, v6
	s_mov_b64 s[10:11], -1
	v_mov_b32_e32 v0, v2
	s_and_saveexec_b64 s[8:9], vcc
	s_cbranch_execz .LBB0_512
	v_lshrrev_b32_e32 v0, 9, v6
	v_add_u32_e32 v6, -1, v0
	v_lshrrev_b32_e32 v7, 1, v6
	v_add_u32_e32 v8, 1, v7
	v_cmp_lt_u32_e32 vcc, 5, v6
	v_mov_b32_e32 v11, 0
	v_mov_b64_e32 v[6:7], v[2:3]
	s_and_saveexec_b64 s[10:11], vcc
	s_cbranch_execz .LBB0_508
	s_add_i32 s27, s4, 0x2000
	s_add_i32 s29, s4, 0x4000
	s_add_i32 s31, s4, 0x6000
	v_and_b32_e32 v9, -4, v8
	s_mov_b32 s28, s27
	s_mov_b32 s30, s29
	s_mov_b32 s33, s31
	v_lshl_add_u32 v10, v2, 2, s18
	s_mov_b32 s34, 0
	s_mov_b64 s[12:13], 0
	v_mov_b64_e32 v[6:7], v[2:3]

.LBB0_516:
	s_or_b64 exec, exec, s[2:3]
	s_lshl_b32 s2, s26, 12
	s_lshl_b32 s3, s23, 8
	v_ashrrev_i32_e32 v4, 1, v2
	s_add_i32 s4, s3, s2
	v_readlane_b32 s2, v246, 26
	v_ashrrev_i32_e32 v5, 31, v4
	v_readlane_b32 s3, v246, 27
	v_and_b32_e32 v17, 1, v2
	v_lshl_add_u64 v[2:3], v[4:5], 0, s[4:5]
	v_mov_b64_e32 v[8:9], s[2:3]
	v_mad_u64_u32 v[8:9], s[2:3], v2, s20, v[8:9]
	v_mad_i32_i24 v9, v3, s20, v9
	v_lshl_add_u64 v[2:3], v[6:7], 1, v[8:9]
	v_lshlrev_b32_e32 v0, 6, v17
	v_lshl_add_u64 v[2:3], v[2:3], 0, v[0:1]
	s_waitcnt lgkmcnt(0)
	s_barrier
	v_and_b32_e32 v3, 64, v16
	v_xor_b32_e32 v2, 1, v16
	v_add_u32_e32 v3, 64, v3
	v_cmp_lt_i32_e32 vcc, v2, v3
	s_mov_b32 s4, 0
	v_mov_b32_e32 v42, 0xff800000
	v_cndmask_b32_e32 v2, v16, v2, vcc
	v_mov_b32_e32 v37, 0
	v_mov_b32_e32 v5, 0
	v_mov_b32_e32 v0, 0
	v_mov_b32_e32 v19, 0xff800000
	v_lshl_add_u32 v18, v17, 7, s18
	v_lshlrev_b32_e32 v20, 2, v2
	v_mov_b32_e32 v43, 0xff800000
	s_waitcnt vmcnt(3)
	v_lshlrev_b32_e32 v21, 16, v72
	v_and_b32_e32 v22, 0xffff0000, v72
	v_lshlrev_b32_e32 v23, 16, v73
	v_and_b32_e32 v24, 0xffff0000, v73
	v_lshlrev_b32_e32 v25, 16, v74
	v_and_b32_e32 v26, 0xffff0000, v74
	v_lshlrev_b32_e32 v27, 16, v75
	v_and_b32_e32 v28, 0xffff0000, v75
	s_waitcnt vmcnt(2)
	v_lshlrev_b32_e32 v29, 16, v76
	v_and_b32_e32 v30, 0xffff0000, v76
	v_lshlrev_b32_e32 v31, 16, v77
	v_and_b32_e32 v32, 0xffff0000, v77
	v_lshlrev_b32_e32 v33, 16, v78
	v_and_b32_e32 v34, 0xffff0000, v78
	v_lshlrev_b32_e32 v35, 16, v79
	v_and_b32_e32 v36, 0xffff0000, v79
	s_waitcnt vmcnt(1)
	v_lshlrev_b32_e32 v38, 16, v80
	v_and_b32_e32 v39, 0xffff0000, v80
	v_lshlrev_b32_e32 v40, 16, v81
	v_and_b32_e32 v41, 0xffff0000, v81
	v_lshlrev_b32_e32 v2, 16, v82
	v_and_b32_e32 v3, 0xffff0000, v82
	v_lshlrev_b32_e32 v6, 16, v83
	v_and_b32_e32 v7, 0xffff0000, v83
	s_waitcnt vmcnt(0)
	v_lshlrev_b32_e32 v8, 16, v84
	v_and_b32_e32 v9, 0xffff0000, v84
	v_lshlrev_b32_e32 v10, 16, v85
	v_and_b32_e32 v11, 0xffff0000, v85
	v_lshlrev_b32_e32 v12, 16, v86
	v_and_b32_e32 v13, 0xffff0000, v86
	v_lshlrev_b32_e32 v14, 16, v87
	v_and_b32_e32 v15, 0xffff0000, v87
